# combined version plus DPP moves for the three row-statistics hops in the mLSTM output phase
# baseline (speedup 1.0000x reference)
; #define LAS __attribute__((address_space(3)))
; __device__ __forceinline__ unsigned pk2(float lo, float hi) { f32x2_t v = {lo, hi}; bf16x2_t b = __builtin_convertvector(v, bf16x2_t); return __builtin_bit_cast(unsigned, b); }
; __device__ __forceinline__ f32x4 mfma16(bf16x8 a, bf16x8 b, f32x4 c) { return __builtin_amdgcn_mfma_f32_16x16x32_bf16(a, b, c, 0, 0, 0); }
; __device__ __forceinline__ void mlstm_unit(const Args& a, LAS unsigned char* lds, int b, int h, int tid_in, int wave, int lane_in) {
;     ...
;         {
;             const float dec = __expf(mstate - M63);
; #pragma unroll
;             for (int et = 0; et < 9; ++et) {
;                 if ((et & 1) == 0) asm volatile("" ::: "memory");
;                 Creg[et] = Creg[et] * dec;
; #pragma unroll
;                 for (int kk = 0; kk < 2; ++kk) Creg[et] = mfma16(*(const LAS bf16x8*)(vT + (16 * et + fr) * TS + 8 * ((4 * kk + fq) ^ (et & 7))), *(const LAS bf16x8*)(kTw + (16 * wave + fr) * TS + 8 * ((4 * kk + fq) ^ (wave & 7))), Creg[et]);
;                 { const unsigned w0 = pk2(Creg[et][0], Creg[et][1]), w1 = pk2(Creg[et][2], Creg[et][3]); const int e0 = 16 * et + 4 * fq, dcol = 16 * wave + fr;
;                   C_s[(e0 + 0) * QS + dcol] = (bf16)(w0 & 0xffffu); C_s[(e0 + 1) * QS + dcol] = (bf16)(w0 >> 16); C_s[(e0 + 2) * QS + dcol] = (bf16)(w1 & 0xffffu); C_s[(e0 + 3) * QS + dcol] = (bf16)(w1 >> 16); }
;             }
;         }
.LBB0_1069:
	v_readlane_b32 s4, v254, 9
	v_mad_u32_u24 v106, v137, s79, 0
	s_nop 2
	v_subrev_f32_e32 v88, s50, v166
	v_or_b32_e32 v89, s4, v137
	v_mul_lo_u32 v90, v89, s79
	v_add_u32_e32 v102, 0, v90
	v_add_u32_e32 v90, v106, v136
	ds_read_b128 v[90:93], v90 offset:53248
	v_xor_b32_e32 v94, s39, v168
	v_mul_f32_e32 v88, 0x3fb8aa3b, v88
	v_lshl_add_u32 v107, v94, 4, v102
	v_exp_f32_e32 v88, v88
	ds_read_b128 v[94:97], v107 offset:34816
	v_lshlrev_b32_e32 v108, 4, v116
	v_add_u32_e32 v98, v106, v108
	ds_read_b128 v[98:101], v98 offset:53248
	v_pk_mul_f32 v[50:51], v[50:51], v[88:89] op_sel_hi:[1,0]
	v_pk_mul_f32 v[48:49], v[48:49], v[88:89] op_sel_hi:[1,0]
	s_movk_i32 s4, 0x440
	v_mul_lo_u32 v110, v168, s4
	s_waitcnt lgkmcnt(1)
	v_mfma_f32_16x16x32_bf16 v[48:51], v[90:93], v[94:97], v[48:51]
	v_xor_b32_e32 v90, s39, v116
	v_lshl_add_u32 v109, v90, 4, v102
	ds_read_b128 v[90:93], v109 offset:34816
	s_waitcnt lgkmcnt(0)
	v_mfma_f32_16x16x32_bf16 v[48:51], v[98:101], v[90:93], v[48:51]
	v_lshlrev_b32_e32 v89, 1, v89
	v_add3_u32 v92, s58, v110, v89
	v_xad_u32 v98, v108, 16, v106
	s_nop 4
	v_cvt_pk_bf16_f32 v90, v48, v49
	v_cvt_pk_bf16_f32 v91, v50, v51
	ds_write_b16 v92, v90
	ds_write_b16_d16_hi v92, v90 offset:272
	ds_write_b16 v92, v91 offset:544
	ds_write_b16_d16_hi v92, v91 offset:816
	v_xad_u32 v90, v136, 16, v106
	ds_read_b128 v[90:93], v90 offset:55552
	ds_read_b128 v[94:97], v107 offset:34816
	ds_read_b128 v[98:101], v98 offset:55552
	ds_read_b128 v[102:105], v109 offset:34816
	v_pk_mul_f32 v[46:47], v[46:47], v[88:89] op_sel_hi:[1,0]
	v_pk_mul_f32 v[44:45], v[44:45], v[88:89] op_sel_hi:[1,0]
	v_pk_mul_f32 v[54:55], v[54:55], v[88:89] op_sel_hi:[1,0]
	v_pk_mul_f32 v[52:53], v[52:53], v[88:89] op_sel_hi:[1,0]
	s_waitcnt lgkmcnt(2)
	v_mfma_f32_16x16x32_bf16 v[44:47], v[90:93], v[94:97], v[44:47]
	v_add3_u32 v92, s85, v110, v89
	v_pk_mul_f32 v[58:59], v[58:59], v[88:89] op_sel_hi:[1,0]
	v_pk_mul_f32 v[56:57], v[56:57], v[88:89] op_sel_hi:[1,0]
	s_waitcnt lgkmcnt(0)
	v_mfma_f32_16x16x32_bf16 v[44:47], v[98:101], v[102:105], v[44:47]
	v_xad_u32 v98, v108, 32, v106
	v_pk_mul_f32 v[62:63], v[62:63], v[88:89] op_sel_hi:[1,0]
	v_pk_mul_f32 v[60:61], v[60:61], v[88:89] op_sel_hi:[1,0]
	v_pk_mul_f32 v[66:67], v[66:67], v[88:89] op_sel_hi:[1,0]
	v_pk_mul_f32 v[64:65], v[64:65], v[88:89] op_sel_hi:[1,0]
	s_nop 2
	v_cvt_pk_bf16_f32 v90, v44, v45
	v_cvt_pk_bf16_f32 v91, v46, v47
	ds_write_b16 v92, v90
	ds_write_b16_d16_hi v92, v90 offset:272
	ds_write_b16 v92, v91 offset:544
	ds_write_b16_d16_hi v92, v91 offset:816
	v_xad_u32 v90, v136, 32, v106
	ds_read_b128 v[90:93], v90 offset:57856
	ds_read_b128 v[94:97], v107 offset:34816
	ds_read_b128 v[98:101], v98 offset:57856
	ds_read_b128 v[102:105], v109 offset:34816
	s_waitcnt lgkmcnt(2)
	v_mfma_f32_16x16x32_bf16 v[52:55], v[90:93], v[94:97], v[52:55]
	v_add3_u32 v92, s86, v110, v89
	v_pk_mul_f32 v[70:71], v[70:71], v[88:89] op_sel_hi:[1,0]
	v_pk_mul_f32 v[68:69], v[68:69], v[88:89] op_sel_hi:[1,0]
	s_waitcnt lgkmcnt(0)
	v_mfma_f32_16x16x32_bf16 v[52:55], v[98:101], v[102:105], v[52:55]
	v_xad_u32 v98, v108, 48, v106
	v_pk_mul_f32 v[78:79], v[78:79], v[88:89] op_sel_hi:[1,0]
	v_pk_mul_f32 v[76:77], v[76:77], v[88:89] op_sel_hi:[1,0]
	v_pk_mul_f32 v[74:75], v[74:75], v[88:89] op_sel_hi:[1,0]
	s_nop 3
	v_cvt_pk_bf16_f32 v90, v52, v53
	v_cvt_pk_bf16_f32 v91, v54, v55
	ds_write_b16 v92, v90
	ds_write_b16_d16_hi v92, v90 offset:272
	ds_write_b16 v92, v91 offset:544
	ds_write_b16_d16_hi v92, v91 offset:816
	v_xad_u32 v90, v136, 48, v106
	ds_read_b128 v[90:93], v90 offset:60160
	ds_read_b128 v[94:97], v107 offset:34816
	ds_read_b128 v[98:101], v98 offset:60160
	ds_read_b128 v[102:105], v109 offset:34816
	s_waitcnt lgkmcnt(2)
	v_mfma_f32_16x16x32_bf16 v[56:59], v[90:93], v[94:97], v[56:59]
	v_add3_u32 v92, s87, v110, v89
	v_pk_mul_f32 v[72:73], v[72:73], v[88:89] op_sel_hi:[1,0]
	v_ashrrev_i32_e32 v88, 3, v167
	s_waitcnt lgkmcnt(0)
	v_mfma_f32_16x16x32_bf16 v[56:59], v[98:101], v[102:105], v[56:59]
	v_xad_u32 v98, v108, 64, v106
	v_add_u32_e32 v88, s34, v88
	s_waitcnt vmcnt(0)
	v_lshlrev_b32_e32 v122, 16, v85
	v_and_b32_e32 v124, 0xffff0000, v85
	s_nop 2
	v_cvt_pk_bf16_f32 v90, v56, v57
	v_cvt_pk_bf16_f32 v91, v58, v59
	ds_write_b16 v92, v90
	ds_write_b16_d16_hi v92, v90 offset:272
	ds_write_b16 v92, v91 offset:544
	ds_write_b16_d16_hi v92, v91 offset:816
	v_xad_u32 v90, v136, 64, v106
	ds_read_b128 v[90:93], v90 offset:62464
	ds_read_b128 v[94:97], v107 offset:34816
	ds_read_b128 v[98:101], v98 offset:62464
	ds_read_b128 v[102:105], v109 offset:34816
	s_waitcnt lgkmcnt(2)
	v_mfma_f32_16x16x32_bf16 v[60:63], v[90:93], v[94:97], v[60:63]
	v_add3_u32 v90, s88, v110, v89
	s_waitcnt lgkmcnt(0)
	v_mfma_f32_16x16x32_bf16 v[60:63], v[98:101], v[102:105], v[60:63]
	v_xad_u32 v98, v108, s89, v106
	s_nop 6
	v_cvt_pk_bf16_f32 v91, v60, v61
	v_cvt_pk_bf16_f32 v92, v62, v63
	ds_write_b16 v90, v91
	ds_write_b16_d16_hi v90, v91 offset:272
	ds_write_b16 v90, v92 offset:544
	ds_write_b16_d16_hi v90, v92 offset:816
	v_xad_u32 v90, v136, s89, v106
	ds_read_b128 v[90:93], v90 offset:64768
	ds_read_b128 v[94:97], v107 offset:34816
	ds_read_b128 v[98:101], v98 offset:64768
	ds_read_b128 v[102:105], v109 offset:34816
	s_waitcnt lgkmcnt(2)
	v_mfma_f32_16x16x32_bf16 v[64:67], v[90:93], v[94:97], v[64:67]
	v_add3_u32 v90, s90, v110, v89
	v_add_u32_e32 v106, 0xd000, v106
	s_waitcnt lgkmcnt(0)
; #define LAS __attribute__((address_space(3)))
; __device__ __forceinline__ unsigned pk2(float lo, float hi) { f32x2_t v = {lo, hi}; bf16x2_t b = __builtin_convertvector(v, bf16x2_t); return __builtin_bit_cast(unsigned, b); }
; __device__ __forceinline__ f32x4 mfma16(bf16x8 a, bf16x8 b, f32x4 c) { return __builtin_amdgcn_mfma_f32_16x16x32_bf16(a, b, c, 0, 0, 0); }
; #define LDS_BARRIER() do { asm volatile("s_waitcnt lgkmcnt(0)" ::: "memory"); __builtin_amdgcn_s_barrier(); asm volatile("" ::: "memory"); } while (0)
; __device__ __forceinline__ void mlstm_unit(const Args& a, LAS unsigned char* lds, int b, int h, int tid_in, int wave, int lane_in) {
;     ...
;         {
;             const float dec = __expf(mstate - M63);
; #pragma unroll
;             for (int et = 0; et < 9; ++et) {
;                 if ((et & 1) == 0) asm volatile("" ::: "memory");
;                 Creg[et] = Creg[et] * dec;
; #pragma unroll
;                 for (int kk = 0; kk < 2; ++kk) Creg[et] = mfma16(*(const LAS bf16x8*)(vT + (16 * et + fr) * TS + 8 * ((4 * kk + fq) ^ (et & 7))), *(const LAS bf16x8*)(kTw + (16 * wave + fr) * TS + 8 * ((4 * kk + fq) ^ (wave & 7))), Creg[et]);
;                 { const unsigned w0 = pk2(Creg[et][0], Creg[et][1]), w1 = pk2(Creg[et][2], Creg[et][3]); const int e0 = 16 * et + 4 * fq, dcol = 16 * wave + fr;
;                   C_s[(e0 + 0) * QS + dcol] = (bf16)(w0 & 0xffffu); C_s[(e0 + 1) * QS + dcol] = (bf16)(w0 >> 16); C_s[(e0 + 2) * QS + dcol] = (bf16)(w1 & 0xffffu); C_s[(e0 + 3) * QS + dcol] = (bf16)(w1 >> 16); }
;             }
;         }
;         LDS_BARRIER();
;         {
;             const int jr = lane >> 3, ec = lane & 7, j = 8 * wave + jr;
;             f32x4 nv[4], gv[4];
; #pragma unroll
;             for (int k = 0; k < 4; ++k) { nv[k] = *(const LAS f32x4*)(numS + j * NS + 16 * ec + 4 * k); gv[k] = *(const LAS f32x4*)(hg_s + 16 * ec + 4 * k); }
;             const float den = numS[j * NS + 128];
;             const float dn = fmaxf(fabsf(den), __expf(-(gate[par * 192 + 64 + j] + gate[par * 192 + j])));
;             const float idn = __builtin_amdgcn_rcpf(dn); float ss = 0.f;
; #pragma unroll
;             for (int k = 0; k < 4; ++k) { nv[k] = nv[k] * idn; ss += (nv[k][0] * nv[k][0] + nv[k][1] * nv[k][1]) + (nv[k][2] * nv[k][2] + nv[k][3] * nv[k][3]); }
;             ss += __shfl_xor(ss, 1); ss += __shfl_xor(ss, 2); ss += __shfl_xor(ss, 4);
	v_mfma_f32_16x16x32_bf16 v[64:67], v[98:101], v[102:105], v[64:67]
	v_xad_u32 v98, v108, s91, v106
	s_nop 6
	v_cvt_pk_bf16_f32 v91, v64, v65
	v_cvt_pk_bf16_f32 v92, v66, v67
	ds_write_b16 v90, v91
	ds_write_b16_d16_hi v90, v91 offset:272
	ds_write_b16 v90, v92 offset:544
	ds_write_b16_d16_hi v90, v92 offset:816
	v_xad_u32 v90, v136, s91, v106
	ds_read_b128 v[90:93], v90 offset:13824
	ds_read_b128 v[94:97], v107 offset:34816
	ds_read_b128 v[98:101], v98 offset:13824
	ds_read_b128 v[102:105], v109 offset:34816
	s_waitcnt lgkmcnt(2)
	v_mfma_f32_16x16x32_bf16 v[68:71], v[90:93], v[94:97], v[68:71]
	v_add3_u32 v90, s92, v110, v89
	s_waitcnt lgkmcnt(0)
	v_mfma_f32_16x16x32_bf16 v[68:71], v[98:101], v[102:105], v[68:71]
	v_xad_u32 v98, v108, s74, v106
	s_nop 6
	v_cvt_pk_bf16_f32 v91, v68, v69
	v_cvt_pk_bf16_f32 v92, v70, v71
	ds_write_b16 v90, v91
	ds_write_b16_d16_hi v90, v91 offset:272
	ds_write_b16 v90, v92 offset:544
	ds_write_b16_d16_hi v90, v92 offset:816
	v_xad_u32 v90, v136, s74, v106
	ds_read_b128 v[90:93], v90 offset:16128
	ds_read_b128 v[94:97], v107 offset:34816
	ds_read_b128 v[98:101], v98 offset:16128
	ds_read_b128 v[102:105], v109 offset:34816
	s_waitcnt lgkmcnt(2)
	v_mfma_f32_16x16x32_bf16 v[76:79], v[90:93], v[94:97], v[76:79]
	v_add3_u32 v90, s93, v110, v89
	v_add_u32_e32 v91, v106, v136
	v_add3_u32 v89, s94, v110, v89
	s_waitcnt lgkmcnt(0)
	v_mfma_f32_16x16x32_bf16 v[76:79], v[98:101], v[102:105], v[76:79]
	v_add_u32_e32 v98, v106, v108
	s_nop 6
	v_cvt_pk_bf16_f32 v92, v76, v77
	v_cvt_pk_bf16_f32 v93, v78, v79
	ds_write_b16 v90, v92
	ds_write_b16_d16_hi v90, v92 offset:272
	ds_write_b16 v90, v93 offset:544
	ds_write_b16_d16_hi v90, v93 offset:816
	ds_read_b128 v[90:93], v91 offset:18432
	ds_read_b128 v[94:97], v107 offset:34816
	ds_read_b128 v[98:101], v98 offset:18432
	ds_read_b128 v[102:105], v109 offset:34816
	s_waitcnt lgkmcnt(2)
	v_mfma_f32_16x16x32_bf16 v[72:75], v[90:93], v[94:97], v[72:75]
	s_waitcnt lgkmcnt(0)
	v_mfma_f32_16x16x32_bf16 v[72:75], v[98:101], v[102:105], v[72:75]
	s_nop 7
	v_cvt_pk_bf16_f32 v90, v72, v73
	v_cvt_pk_bf16_f32 v91, v74, v75
	ds_write_b16 v89, v90
	ds_write_b16_d16_hi v89, v90 offset:272
	ds_write_b16 v89, v91 offset:544
	ds_write_b16_d16_hi v89, v91 offset:816
	s_waitcnt lgkmcnt(0)
	s_barrier
	v_mul_lo_u32 v89, v88, s84
	v_lshl_add_u32 v88, v88, 2, s13
	ds_read2st64_b32 v[92:93], v88 offset1:1
	v_add_u32_e32 v94, 0, v89
	v_lshlrev_b32_e32 v89, 6, v167
	v_and_b32_e32 v95, 0x1c0, v89
	v_add_u32_e32 v100, v94, v95
	ds_read_b128 v[88:91], v100
	ds_read_b32 v94, v94 offset:512
	s_waitcnt lgkmcnt(2)
	v_add_f32_e32 v92, v93, v92
	v_mul_f32_e32 v92, 0xbfb8aa3b, v92
	v_exp_f32_e32 v92, v92
	v_add_u32_e32 v93, 0, v95
	v_add_u32_e32 v109, 0x1fa00, v93
	s_waitcnt lgkmcnt(0)
	v_max_f32_e64 v93, |v94|, |v94|
	v_max_f32_e32 v92, v93, v92
	v_rcp_f32_e32 v108, v92
	ds_read_b128 v[92:95], v100 offset:16
	ds_read_b128 v[96:99], v100 offset:32
	ds_read_b128 v[100:103], v100 offset:48
	ds_read_b128 v[104:107], v109
	v_pk_mul_f32 v[110:111], v[88:89], v[108:109] op_sel_hi:[1,0]
	v_pk_mul_f32 v[112:113], v[90:91], v[108:109] op_sel_hi:[1,0]
	v_pk_mul_f32 v[90:91], v[110:111], v[110:111]
	v_pk_mul_f32 v[88:89], v[112:113], v[112:113]
	s_waitcnt lgkmcnt(3)
	v_pk_mul_f32 v[116:117], v[94:95], v[108:109] op_sel_hi:[1,0]
	v_pk_mov_b32 v[114:115], v[90:91], v[88:89] op_sel:[1,0]
	v_mov_b32_e32 v91, v89
	v_pk_add_f32 v[88:89], v[114:115], v[90:91]
	v_pk_mul_f32 v[114:115], v[92:93], v[108:109] op_sel_hi:[1,0]
	v_pk_add_f32 v[88:89], v[88:89], v[88:89] op_sel_hi:[0,1]
	v_pk_mul_f32 v[90:91], v[116:117], v[116:117]
	v_pk_mul_f32 v[92:93], v[114:115], v[114:115]
	s_waitcnt lgkmcnt(2)
	v_pk_mul_f32 v[120:121], v[96:97], v[108:109] op_sel_hi:[1,0]
	v_pk_mov_b32 v[94:95], v[92:93], v[90:91] op_sel:[1,0]
	v_mov_b32_e32 v93, v91
	v_pk_mul_f32 v[118:119], v[98:99], v[108:109] op_sel_hi:[1,0]
	v_mul_f32_e32 v88, v120, v120
	v_pk_add_f32 v[90:91], v[94:95], v[92:93]
	v_pk_fma_f32 v[92:93], v[120:121], v[120:121], v[88:89] op_sel_hi:[1,1,0]
	v_mul_f32_e32 v88, v118, v118
	v_pk_add_f32 v[90:91], v[90:91], v[90:91] op_sel_hi:[0,1]
	v_pk_fma_f32 v[94:95], v[118:119], v[118:119], v[88:89] op_sel_hi:[1,1,0]
	s_waitcnt lgkmcnt(1)
	v_pk_mul_f32 v[102:103], v[102:103], v[108:109] op_sel_hi:[1,0]
	v_pk_mul_f32 v[100:101], v[100:101], v[108:109] op_sel_hi:[1,0]
	v_mul_f32_e32 v88, v102, v102
	v_mul_f32_e32 v92, v100, v100
	v_mul_f32_e32 v94, v101, v101
	v_mul_f32_e32 v90, v103, v103
	v_pk_add_f32 v[92:93], v[92:93], v[94:95]
	v_pk_add_f32 v[88:89], v[88:89], v[90:91]
	s_nop 0
	v_pk_add_f32 v[88:89], v[92:93], v[88:89]
	s_nop 0
	v_add_f32_e32 v88, v88, v89
	s_nop 0
	s_waitcnt lgkmcnt(0)
	s_nop 1
	v_mov_b32_dpp v89, v88 quad_perm:[1,0,3,2] row_mask:0xf bank_mask:0xf
	v_add_f32_e32 v88, v88, v89
	s_nop 0
	s_waitcnt lgkmcnt(0)
	s_nop 1
	v_mov_b32_dpp v89, v88 quad_perm:[2,3,0,1] row_mask:0xf bank_mask:0xf
	v_add_f32_e32 v88, v88, v89
	s_nop 0
	s_waitcnt lgkmcnt(0)
; #define GAS __attribute__((address_space(1)))
; __device__ __forceinline__ unsigned pk2(float lo, float hi) { f32x2_t v = {lo, hi}; bf16x2_t b = __builtin_convertvector(v, bf16x2_t); return __builtin_bit_cast(unsigned, b); }
; __device__ __forceinline__ void mlstm_unit(const Args& a, LAS unsigned char* lds, int b, int h, int tid_in, int wave, int lane_in) {
;     ...
;             ss += __shfl_xor(ss, 1); ss += __shfl_xor(ss, 2); ss += __shfl_xor(ss, 4);
;             const float rs = rsqrtf(ss * (1.f / 128.f) + EPS);
;             u32x4 yo[2];
; #pragma unroll
;             for (int k = 0; k < 4; ++k) {
;                 const unsigned w0 = ow2[k >> 1][2 * (k & 1)], w1 = ow2[k >> 1][2 * (k & 1) + 1];
;                 const float o0 = bflo(w0), o1 = bfhi(w0), o2 = bflo(w1), o3 = bfhi(w1);
;                 const float y0 = nv[k][0] * rs * gv[k][0] * __builtin_amdgcn_rcpf(1.f + __expf(-o0)), y1 = nv[k][1] * rs * gv[k][1] * __builtin_amdgcn_rcpf(1.f + __expf(-o1));
;                 const float y2 = nv[k][2] * rs * gv[k][2] * __builtin_amdgcn_rcpf(1.f + __expf(-o2)), y3 = nv[k][3] * rs * gv[k][3] * __builtin_amdgcn_rcpf(1.f + __expf(-o3));
;                 yo[k >> 1][2 * (k & 1)] = pk2(y0, y1); yo[k >> 1][2 * (k & 1) + 1] = pk2(y2, y3);
;             }
;             GAS char* yp = (GAS char*)Y + (size_t)(rowb + t0) * (DM * 2) + (size_t)vo_y;
;             *(GAS u32x4*)yp = yo[0]; *(GAS u32x4*)(yp + 16) = yo[1];
	s_nop 1
	v_mov_b32_dpp v89, v88 row_half_mirror row_mask:0xf bank_mask:0xf
	v_add_f32_e32 v88, v88, v89
	v_fmamk_f32 v88, v88, 0x3c000000, v138
	v_mul_f32_e32 v89, 0x4b800000, v88
	v_cmp_gt_f32_e32 vcc, s76, v88
	s_nop 1
	v_cndmask_b32_e32 v88, v88, v89, vcc
	v_rsq_f32_e32 v108, v88
	ds_read_b128 v[88:91], v109 offset:16
	ds_read_b128 v[92:95], v109 offset:32
	ds_read_b128 v[96:99], v109 offset:48
	v_mul_f32_e32 v109, 0x45800000, v108
	v_cndmask_b32_e32 v108, v108, v109, vcc
	v_lshlrev_b32_e32 v109, 16, v84
	v_mul_f32_e32 v109, 0xbfb8aa3b, v109
	v_exp_f32_e32 v109, v109
	v_and_b32_e32 v84, 0xffff0000, v84
	v_mul_f32_e32 v84, 0xbfb8aa3b, v84
	v_exp_f32_e32 v123, v84
	v_add_f32_e32 v84, 1.0, v109
	v_pk_mul_f32 v[110:111], v[110:111], v[108:109] op_sel_hi:[1,0]
	v_mul_f32_e32 v109, 0xbfb8aa3b, v122
	v_exp_f32_e32 v109, v109
	v_mul_f32_e32 v122, 0xbfb8aa3b, v124
	v_exp_f32_e32 v122, v122
	v_add_f32_e32 v85, 1.0, v123
	v_rcp_f32_e32 v84, v84
	v_rcp_f32_e32 v85, v85
	v_add_f32_e32 v109, 1.0, v109
	v_pk_mul_f32 v[104:105], v[104:105], v[110:111]
	v_rcp_f32_e32 v110, v109
	v_add_f32_e32 v109, 1.0, v122
	v_rcp_f32_e32 v111, v109
	v_pk_mul_f32 v[84:85], v[84:85], v[104:105]
	v_pk_mul_f32 v[104:105], v[112:113], v[108:109] op_sel_hi:[1,0]
	v_cvt_pk_bf16_f32 v84, v84, v85
	v_pk_mul_f32 v[104:105], v[106:107], v[104:105]
	v_lshlrev_b32_e32 v106, 16, v87
	v_pk_mul_f32 v[104:105], v[110:111], v[104:105]
	v_and_b32_e32 v107, 0xffff0000, v87
	v_cvt_pk_bf16_f32 v85, v104, v105
	v_lshlrev_b32_e32 v104, 16, v86
	v_and_b32_e32 v86, 0xffff0000, v86
	v_mul_f32_e32 v104, 0xbfb8aa3b, v104
	v_mul_f32_e32 v86, 0xbfb8aa3b, v86
	v_exp_f32_e32 v104, v104
	v_exp_f32_e32 v105, v86
	v_mul_f32_e32 v106, 0xbfb8aa3b, v106
	v_mul_f32_e32 v107, 0xbfb8aa3b, v107
	v_exp_f32_e32 v106, v106
	v_exp_f32_e32 v107, v107
	v_add_f32_e32 v86, 1.0, v104
	v_add_f32_e32 v87, 1.0, v105
	v_rcp_f32_e32 v86, v86
	v_rcp_f32_e32 v87, v87
	v_pk_mul_f32 v[104:105], v[114:115], v[108:109] op_sel_hi:[1,0]
	s_andn2_b64 vcc, exec, s[2:3]
	s_waitcnt lgkmcnt(2)
	v_pk_mul_f32 v[88:89], v[88:89], v[104:105]
	v_add_f32_e32 v104, 1.0, v106
	v_add_f32_e32 v105, 1.0, v107
	v_rcp_f32_e32 v104, v104
	v_rcp_f32_e32 v105, v105
	v_pk_mul_f32 v[86:87], v[86:87], v[88:89]
	v_pk_mul_f32 v[88:89], v[116:117], v[108:109] op_sel_hi:[1,0]
	v_cvt_pk_bf16_f32 v86, v86, v87
	v_pk_mul_f32 v[88:89], v[90:91], v[88:89]
	v_lshlrev_b32_e32 v90, 16, v81
	v_pk_mul_f32 v[88:89], v[104:105], v[88:89]
	v_and_b32_e32 v91, 0xffff0000, v81
	v_cvt_pk_bf16_f32 v87, v88, v89
	v_lshlrev_b32_e32 v88, 16, v80
	v_and_b32_e32 v80, 0xffff0000, v80
	v_mul_f32_e32 v88, 0xbfb8aa3b, v88
	v_mul_f32_e32 v80, 0xbfb8aa3b, v80
	v_exp_f32_e32 v88, v88
	v_exp_f32_e32 v89, v80
	v_mul_f32_e32 v90, 0xbfb8aa3b, v90
	v_mul_f32_e32 v91, 0xbfb8aa3b, v91
	v_exp_f32_e32 v90, v90
	v_exp_f32_e32 v91, v91
	v_add_f32_e32 v80, 1.0, v88
	v_add_f32_e32 v81, 1.0, v89
	v_rcp_f32_e32 v80, v80
	v_rcp_f32_e32 v81, v81
	v_add_f32_e32 v90, 1.0, v90
	v_add_f32_e32 v91, 1.0, v91
	v_pk_mul_f32 v[88:89], v[120:121], v[108:109] op_sel_hi:[1,0]
	v_rcp_f32_e32 v90, v90
	v_rcp_f32_e32 v91, v91
	s_waitcnt lgkmcnt(1)
	v_pk_mul_f32 v[88:89], v[92:93], v[88:89]
	global_store_dwordx4 v[126:127], v[84:87], off offset:-16
	v_pk_mul_f32 v[80:81], v[80:81], v[88:89]
	v_pk_mul_f32 v[88:89], v[118:119], v[108:109] op_sel_hi:[1,0]
	v_cvt_pk_bf16_f32 v80, v80, v81
	v_pk_mul_f32 v[88:89], v[94:95], v[88:89]
	s_nop 0
	v_pk_mul_f32 v[88:89], v[90:91], v[88:89]
	v_lshlrev_b32_e32 v90, 16, v83
	v_cvt_pk_bf16_f32 v81, v88, v89
	v_lshlrev_b32_e32 v88, 16, v82
	v_and_b32_e32 v82, 0xffff0000, v82
	v_mul_f32_e32 v88, 0xbfb8aa3b, v88
	v_mul_f32_e32 v82, 0xbfb8aa3b, v82
	v_exp_f32_e32 v88, v88
	v_exp_f32_e32 v89, v82
	v_and_b32_e32 v91, 0xffff0000, v83
	v_mul_f32_e32 v90, 0xbfb8aa3b, v90
	v_mul_f32_e32 v91, 0xbfb8aa3b, v91
	v_exp_f32_e32 v90, v90
	v_exp_f32_e32 v91, v91
	v_add_f32_e32 v82, 1.0, v88
	v_add_f32_e32 v83, 1.0, v89
	v_rcp_f32_e32 v82, v82
	v_rcp_f32_e32 v83, v83
	v_add_f32_e32 v90, 1.0, v90
	v_add_f32_e32 v91, 1.0, v91
	v_pk_mul_f32 v[88:89], v[100:101], v[108:109] op_sel_hi:[1,0]
	v_rcp_f32_e32 v90, v90
	v_rcp_f32_e32 v91, v91
	s_waitcnt lgkmcnt(0)
	v_pk_mul_f32 v[88:89], v[96:97], v[88:89]
	s_nop 0
	v_pk_mul_f32 v[82:83], v[82:83], v[88:89]
	v_pk_mul_f32 v[88:89], v[102:103], v[108:109] op_sel_hi:[1,0]
	v_cvt_pk_bf16_f32 v82, v82, v83
	v_pk_mul_f32 v[88:89], v[98:99], v[88:89]
	s_nop 0
	v_pk_mul_f32 v[88:89], v[90:91], v[88:89]
	s_nop 0
	v_cvt_pk_bf16_f32 v83, v88, v89
	global_store_dwordx4 v[126:127], v[80:83], off
	s_cbranch_vccnz .LBB0_1024
; __device__ __forceinline__ float scan_add(float v, int lane) {
; #pragma unroll
;     for (int o = 1; o < 64; o <<= 1) { const float t = __shfl_up(v, o); if (lane >= o) v += t; }
;     return v;
; }
; __device__ __forceinline__ float scan_max(float v, int lane) {
; #pragma unroll
;     for (int o = 1; o < 64; o <<= 1) { const float t = __shfl_up(v, o); if (lane >= o) v = fmaxf(v, t); }
;     return v;
; }
; __device__ __forceinline__ void mlstm_unit(const Args& a, LAS unsigned char* lds, int b, int h, int tid_in, int wave, int lane_in) {
;     ...
;         mstate = bL + M63;
;         if (c + 1 < 32) {
;             const float mi = bf2f(gmi) + ib, mf = bf2f(gmf) + fb; const float lf = fminf(mf, 0.f) - __logf(1.f + __expf(-fabsf(mf)));
;             bc = scan_add(lf, lane); av = mi - bc; pm = scan_max(av, lane); }
	s_nop 0
	v_lshlrev_b32_e32 v80, 16, v148
	v_add_f32_e32 v80, v145, v80
	v_mul_f32_e64 v81, |v80|, s75
	v_exp_f32_e32 v81, v81
	v_min_f32_e32 v80, 0, v80
	v_cmp_gt_i32_e64 s[10:11], 2, v167
	v_cmp_gt_i32_e64 s[12:13], 4, v167
	v_add_f32_e32 v81, 1.0, v81
	v_cmp_gt_f32_e32 vcc, s76, v81
	v_cmp_gt_i32_e64 s[14:15], 8, v167
	v_cmp_gt_i32_e64 s[16:17], 16, v167
	v_cndmask_b32_e64 v82, 0, 32, vcc
	v_ldexp_f32 v81, v81, v82
	v_log_f32_e32 v81, v81
	v_cndmask_b32_e32 v82, 0, v142, vcc
	v_cmp_gt_i32_e64 s[18:19], 32, v167
	v_mul_f32_e32 v83, 0x3f317217, v81
	v_fma_f32 v83, v81, s77, -v83
	v_fmac_f32_e32 v83, 0x3377d1cf, v81
	v_fmac_f32_e32 v83, 0x3f317217, v81
	v_cmp_lt_f32_e64 vcc, |v81|, s78
	s_nop 1
	v_cndmask_b32_e32 v81, v81, v83, vcc
	v_sub_f32_e32 v81, v81, v82
	v_sub_f32_e32 v80, v80, v81
	ds_bpermute_b32 v81, v149, v80
	v_cmp_gt_i32_e32 vcc, 1, v167
	v_lshlrev_b32_e32 v82, 16, v147
	v_add_f32_e32 v82, v144, v82
	s_waitcnt lgkmcnt(0)
	v_add_f32_e32 v81, v80, v81
	v_cndmask_b32_e32 v80, v81, v80, vcc
	ds_bpermute_b32 v81, v150, v80
	s_waitcnt lgkmcnt(0)
	v_add_f32_e32 v81, v80, v81
	v_cndmask_b32_e64 v80, v81, v80, s[10:11]
	ds_bpermute_b32 v81, v151, v80
	s_waitcnt lgkmcnt(0)
	v_add_f32_e32 v81, v80, v81
	v_cndmask_b32_e64 v80, v81, v80, s[12:13]
	ds_bpermute_b32 v81, v152, v80
	s_waitcnt lgkmcnt(0)
	v_add_f32_e32 v81, v80, v81
	v_cndmask_b32_e64 v80, v81, v80, s[14:15]
	ds_bpermute_b32 v81, v153, v80
	s_waitcnt lgkmcnt(0)
	v_add_f32_e32 v81, v80, v81
	v_cndmask_b32_e64 v80, v81, v80, s[16:17]
	ds_bpermute_b32 v81, v154, v80
	s_waitcnt lgkmcnt(0)
	v_add_f32_e32 v81, v80, v81
	v_cndmask_b32_e64 v155, v81, v80, s[18:19]
	v_sub_f32_e32 v156, v82, v155
	ds_bpermute_b32 v80, v149, v156
	s_waitcnt lgkmcnt(0)
	v_max_f32_e32 v80, v80, v80
	v_max_f32_e32 v80, v156, v80
	v_cndmask_b32_e32 v80, v80, v156, vcc
	ds_bpermute_b32 v81, v150, v80
	s_waitcnt lgkmcnt(0)
	v_max_f32_e32 v81, v81, v81
	v_max_f32_e32 v81, v80, v81
	v_cndmask_b32_e64 v80, v81, v80, s[10:11]
	ds_bpermute_b32 v81, v151, v80
	s_waitcnt lgkmcnt(0)
	v_max_f32_e32 v81, v81, v81
	v_max_f32_e32 v81, v80, v81
	v_cndmask_b32_e64 v80, v81, v80, s[12:13]
	ds_bpermute_b32 v81, v152, v80
	s_waitcnt lgkmcnt(0)
	v_max_f32_e32 v81, v81, v81
	v_max_f32_e32 v81, v80, v81
	v_cndmask_b32_e64 v80, v81, v80, s[14:15]
	ds_bpermute_b32 v81, v153, v80
	s_waitcnt lgkmcnt(0)
	v_max_f32_e32 v81, v81, v81
	v_max_f32_e32 v81, v80, v81
	v_cndmask_b32_e64 v80, v81, v80, s[16:17]
	ds_bpermute_b32 v81, v154, v80
	v_max_f32_e32 v82, v80, v80
	s_waitcnt lgkmcnt(0)
	v_max_f32_e32 v81, v81, v81
	v_max_f32_e32 v81, v82, v81
	v_cndmask_b32_e64 v157, v81, v80, s[18:19]
	s_branch .LBB0_1024
